# H GEMM tile loop rotated: next tile's coordinates, epilogue-constant load and first LDS-DMA stage issued before the current tile's epilogue
# speedup vs baseline: 1.0482x; 1.0049x over previous
.LBB0_1546:
	s_or_b64 exec, exec, s[20:21]
	v_lshlrev_b32_e32 v132, 2, v137
	v_lshlrev_b32_e32 v133, 2, v138
	v_add3_u32 v147, s59, v132, v133
	v_add_u32_e32 v148, s16, v136
	v_mov_b64_e32 v[132:133], s[14:15]
	v_or_b32_e32 v149, s18, v137
	v_mad_i64_i32 v[158:159], s[18:19], v148, s46, v[132:133]
	v_lshl_add_u32 v148, v136, 2, s59
	ds_read_b32 v150, v148
	v_ashrrev_i32_e32 v149, 1, v149
	s_add_i32 s56, s56, 1
	s_mov_b32 s96, s16
	s_cmp_ge_u32 s56, s54
	s_cbranch_scc0 .Lhr_1550
	s_cmp_eq_u32 s56, s54
	s_cselect_b64 s[16:17], -1, 0
	s_and_b64 s[16:17], s[16:17], s[8:9]
	s_and_b64 s[16:17], s[16:17], s[10:11]
	s_mov_b32 s18, s55
	s_cbranch_execz .Lhr_1551
	s_branch .Lhr_1552

.Lhr_1552:
	s_andn2_b64 vcc, exec, s[16:17]
	s_mov_b64 s[16:17], -1
	s_cbranch_vccnz .Lhr_none
	s_add_i32 s16, s58, s18
	s_mul_hi_i32 s17, s16, 0x2e8ba2e9
	s_lshr_b32 s18, s17, 31
	s_ashr_i32 s17, s17, 5
	s_add_i32 s17, s17, s18
	s_lshl_b32 s19, s17, 3
	s_sub_i32 s18, s76, s19
	s_min_i32 s20, s18, 8
	s_abs_i32 s18, s20
	v_cvt_f32_u32_e32 v236, s18
	s_sub_i32 s22, 0, s18
	s_mulk_i32 s17, 0xb0
	s_sub_i32 s16, s16, s17
	v_rcp_iflag_f32_e32 v236, v236
	s_abs_i32 s17, s16
	s_xor_b32 s21, s16, s20
	s_ashr_i32 s21, s21, 31
	v_mul_f32_e32 v236, 0x4f7ffffe, v236
	v_cvt_u32_f32_e32 v236, v236
	s_nop 0
	v_readfirstlane_b32 s23, v236
	s_mul_i32 s22, s22, s23
	s_mul_hi_u32 s22, s23, s22
	s_add_i32 s23, s23, s22
	s_mul_hi_u32 s22, s17, s23
	s_mul_i32 s23, s22, s18
	s_sub_i32 s17, s17, s23
	s_add_i32 s24, s22, 1
	s_sub_i32 s23, s17, s18
	s_cmp_ge_u32 s17, s18
	s_cselect_b32 s22, s24, s22
	s_cselect_b32 s17, s23, s17
	s_add_i32 s23, s22, 1
	s_cmp_ge_u32 s17, s18
	s_cselect_b32 s17, s23, s22
	s_xor_b32 s17, s17, s21
	s_sub_i32 s18, s17, s21
	s_mul_i32 s17, s18, s20
	s_sub_i32 s16, s16, s17
	s_andn2_b64 vcc, exec, s[70:71]
	s_add_i32 s17, s19, s16
	s_cbranch_vccnz .Lhr_1555
	s_ashr_i32 s16, s17, 31
	s_lshr_b32 s16, s16, 28
	s_add_i32 s16, s17, s16
	s_ashr_i32 s16, s16, 4
	s_add_i32 s16, s17, s16
	s_add_i32 s17, s16, 1
.Lhr_1555:
	s_lshl_b32 s16, s17, 8
	s_lshl_b32 s18, s18, 8
	s_and_saveexec_b64 s[20:21], s[0:1]
	s_xor_b64 s[20:21], exec, s[20:21]
	s_cbranch_execz .Lhr_1557
	s_mul_hi_i32 s17, s17, 0x78787879
	s_lshr_b32 s19, s17, 31
	s_ashr_i32 s17, s17, 3
	s_add_i32 s17, s17, s19
	s_mul_i32 s19, s17, 0xffffef00
	s_add_i32 s19, s19, s16
	s_cmpk_gt_i32 s19, 0xff
	s_cselect_b32 s17, s17, 8
	v_readlane_b32 s19, v254, 44
	s_add_i32 s17, s17, s19
	s_mul_hi_i32 s19, s17, 0x5800
	s_mulk_i32 s17, 0x5800
	s_add_u32 s22, s6, s17
	v_add_u32_e32 v236, s18, v134
	s_addc_u32 s23, s7, s19
	v_ashrrev_i32_e32 v237, 31, v236
	v_lshl_add_u64 v[236:237], v[236:237], 2, s[22:23]
	s_mov_b64 s[22:23], 0x12badc00
	v_lshl_add_u64 v[236:237], v[236:237], 0, s[22:23]
.Lhr_1557:
	s_andn2_saveexec_b64 s[20:21], s[20:21]
	v_add_u32_e32 v236, s16, v134
	v_ashrrev_i32_e32 v237, 31, v236
	v_lshl_add_u64 v[236:237], v[236:237], 2, s[12:13]
	s_or_b64 exec, exec, s[20:21]
	global_load_dword v238, v[236:237], off
	s_lshl_b32 s17, s56, 12
	s_and_b32 s17, s17, 0x1000
	s_add_i32 s59, s17, 0x400
	s_ashr_i32 s19, s18, 31
	s_add_i32 s59, s59, 0x20000
	s_lshl_b64 s[20:21], s[18:19], 11
	s_add_u32 s26, s44, s20
	v_add_u32_e32 v240, s33, v135
	v_lshl_add_u32 v239, v134, 2, s59
	s_addc_u32 s27, s45, s21
	v_readfirstlane_b32 s17, v240
	v_add_u32_e32 v241, 0x2000, v240
	s_mov_b32 m0, s17
	v_readfirstlane_b32 s17, v241
	v_add_u32_e32 v242, 0x400, v135
	v_add_u32_e32 v243, 0x2000, v242
	v_add_u32_e32 v244, s52, v135
	v_add_u32_e32 v245, 0x2000, v244
	v_add_u32_e32 v246, 0x4000, v242
	v_add_u32_e32 v247, 0x6000, v242
	s_waitcnt lgkmcnt(0)
	v_lshl_add_u64 v[236:237], s[26:27], 0, v[0:1]
	global_load_lds_dwordx4 v[236:237], off
	s_mov_b32 m0, s17
	s_ashr_i32 s17, s16, 31
	s_lshl_b64 s[22:23], s[16:17], 11
	s_add_u32 s28, s42, s22
	s_addc_u32 s29, s43, s23
	s_or_b32 s24, s18, 0x80
	s_ashr_i32 s25, s24, 31
	s_lshl_b64 s[24:25], s[24:25], 11
	s_add_u32 s30, s44, s24
	v_lshl_add_u64 v[236:237], s[26:27], 0, v[130:131]
	v_readfirstlane_b32 s17, v242
	s_addc_u32 s31, s45, s25
	s_or_b32 s24, s16, 0x80
	global_load_lds_dwordx4 v[236:237], off
	v_lshl_add_u64 v[236:237], s[28:29], 0, v[0:1]
	s_mov_b32 m0, s17
	v_readfirstlane_b32 s17, v243
	s_ashr_i32 s25, s24, 31
	global_load_lds_dwordx4 v[236:237], off
	v_lshl_add_u64 v[236:237], s[28:29], 0, v[130:131]
	s_mov_b32 m0, s17
	v_readfirstlane_b32 s17, v244
	s_lshl_b64 s[24:25], s[24:25], 11
	global_load_lds_dwordx4 v[236:237], off
	v_lshl_add_u64 v[236:237], s[30:31], 0, v[0:1]
	s_mov_b32 m0, s17
	v_readfirstlane_b32 s17, v245
	s_add_u32 s24, s42, s24
	global_load_lds_dwordx4 v[236:237], off
	v_lshl_add_u64 v[236:237], s[30:31], 0, v[130:131]
	s_mov_b32 m0, s17
	s_addc_u32 s25, s43, s25
	v_readfirstlane_b32 s17, v246
	global_load_lds_dwordx4 v[236:237], off
	v_lshl_add_u64 v[236:237], s[24:25], 0, v[0:1]
	s_mov_b32 m0, s17
	v_readfirstlane_b32 s17, v247
	global_load_lds_dwordx4 v[236:237], off
	v_lshl_add_u64 v[236:237], s[24:25], 0, v[130:131]
	s_mov_b32 m0, s17
	s_nop 0
	global_load_lds_dwordx4 v[236:237], off
	s_mov_b32 s72, 1
	s_branch .Lhr_cont
.Lhr_none:
	s_mov_b32 s72, 0
.Lhr_cont:
	s_waitcnt lgkmcnt(0)
	v_fmamk_f32 v150, v150, 0x3a800000, v206
	v_cmp_gt_f32_e32 vcc, s35, v150
	v_mul_f32_e32 v151, 0x4b800000, v150
	s_nop 0
	v_cndmask_b32_e32 v150, v150, v151, vcc
	v_rsq_f32_e32 v150, v150
	s_nop 0
	v_mul_f32_e32 v151, 0x45800000, v150
	v_cndmask_b32_e32 v160, v150, v151, vcc
	ds_read_b128 v[150:153], v147 offset:1024
	ds_read_b128 v[154:157], v147 offset:1088
	s_waitcnt lgkmcnt(0)
	v_pk_fma_f32 v[126:127], v[126:127], v[160:161], v[150:151] op_sel_hi:[1,0,1]
	s_nop 0
	v_mul_f32_e32 v150, 0xbfb8aa3b, v126
	v_mul_f32_e32 v151, 0xbfb8aa3b, v127
	v_exp_f32_e32 v150, v150
	v_exp_f32_e32 v151, v151
	v_pk_fma_f32 v[122:123], v[122:123], v[160:161], v[154:155] op_sel_hi:[1,0,1]
	v_pk_fma_f32 v[124:125], v[124:125], v[160:161], v[156:157] op_sel_hi:[1,0,1]
	v_add_f32_e32 v150, 1.0, v150
	v_add_f32_e32 v151, 1.0, v151
	v_rcp_f32_e32 v150, v150
	v_rcp_f32_e32 v151, v151
	s_nop 0
	v_pk_mul_f32 v[126:127], v[126:127], v[150:151]
	s_nop 0
	v_pk_mul_f32 v[122:123], v[122:123], v[126:127]
	v_pk_fma_f32 v[126:127], v[128:129], v[160:161], v[152:153] op_sel_hi:[1,0,1]
	s_nop 0
	v_mul_f32_e32 v128, 0xbfb8aa3b, v126
	v_mul_f32_e32 v129, 0xbfb8aa3b, v127
	v_exp_f32_e32 v128, v128
	v_exp_f32_e32 v129, v129
	v_add_f32_e32 v128, 1.0, v128
	v_add_f32_e32 v129, 1.0, v129
	v_rcp_f32_e32 v128, v128
	v_rcp_f32_e32 v129, v129
	s_nop 0
	v_pk_mul_f32 v[126:127], v[126:127], v[128:129]
	s_nop 0
	v_pk_mul_f32 v[124:125], v[124:125], v[126:127]
	v_or_b32_e32 v126, v149, v138
	v_ashrrev_i32_e32 v127, 31, v126
	v_cvt_pk_bf16_f32 v128, v122, v123
	v_lshlrev_b64 v[122:123], 1, v[126:127]
	v_cvt_pk_bf16_f32 v129, v124, v125
	v_lshl_add_u64 v[154:155], v[158:159], 0, v[122:123]
	global_store_dwordx2 v[154:155], v[128:129], off
	ds_read_b128 v[124:127], v147 offset:1536
	ds_read_b128 v[150:153], v147 offset:1600
	s_waitcnt lgkmcnt(0)
	v_pk_fma_f32 v[118:119], v[118:119], v[160:161], v[124:125] op_sel_hi:[1,0,1]
	s_nop 0
	v_mul_f32_e32 v124, 0xbfb8aa3b, v118
	v_mul_f32_e32 v125, 0xbfb8aa3b, v119
	v_exp_f32_e32 v124, v124
	v_exp_f32_e32 v125, v125
	v_pk_fma_f32 v[114:115], v[114:115], v[160:161], v[150:151] op_sel_hi:[1,0,1]
	v_pk_fma_f32 v[116:117], v[116:117], v[160:161], v[152:153] op_sel_hi:[1,0,1]
	v_add_f32_e32 v124, 1.0, v124
	v_add_f32_e32 v125, 1.0, v125
	v_rcp_f32_e32 v124, v124
	v_rcp_f32_e32 v125, v125
	s_nop 0
	v_pk_mul_f32 v[118:119], v[118:119], v[124:125]
	s_nop 0
	v_pk_mul_f32 v[114:115], v[114:115], v[118:119]
	v_pk_fma_f32 v[118:119], v[120:121], v[160:161], v[126:127] op_sel_hi:[1,0,1]
	v_cvt_pk_bf16_f32 v114, v114, v115
	v_mul_f32_e32 v120, 0xbfb8aa3b, v118
	v_mul_f32_e32 v121, 0xbfb8aa3b, v119
	v_exp_f32_e32 v120, v120
	v_exp_f32_e32 v121, v121
	v_add_f32_e32 v120, 1.0, v120
	v_add_f32_e32 v121, 1.0, v121
	v_rcp_f32_e32 v120, v120
	v_rcp_f32_e32 v121, v121
	s_nop 0
	v_pk_mul_f32 v[118:119], v[118:119], v[120:121]
	s_nop 0
	v_pk_mul_f32 v[116:117], v[116:117], v[118:119]
	s_nop 0
	v_cvt_pk_bf16_f32 v115, v116, v117
	global_store_dwordx2 v[154:155], v[114:115], off offset:128
	v_or_b32_e32 v114, 16, v136
	v_add_u32_e32 v114, s96, v114
	v_mad_i64_i32 v[124:125], s[98:99], v114, s46, v[132:133]
	ds_read_b32 v114, v148 offset:64
	s_waitcnt lgkmcnt(0)
	v_fmamk_f32 v114, v114, 0x3a800000, v206
	v_cmp_gt_f32_e32 vcc, s35, v114
	v_mul_f32_e32 v115, 0x4b800000, v114
	s_nop 0
	v_cndmask_b32_e32 v114, v114, v115, vcc
	v_rsq_f32_e32 v114, v114
	s_nop 0
	v_mul_f32_e32 v115, 0x45800000, v114
	v_cndmask_b32_e32 v126, v114, v115, vcc
	ds_read_b128 v[114:117], v147 offset:1024
	ds_read_b128 v[118:121], v147 offset:1088
	s_waitcnt lgkmcnt(0)
	v_pk_fma_f32 v[110:111], v[110:111], v[126:127], v[114:115] op_sel_hi:[1,0,1]
	s_nop 0
	v_mul_f32_e32 v114, 0xbfb8aa3b, v110
	v_mul_f32_e32 v115, 0xbfb8aa3b, v111
	v_exp_f32_e32 v114, v114
	v_exp_f32_e32 v115, v115
	v_pk_fma_f32 v[106:107], v[106:107], v[126:127], v[118:119] op_sel_hi:[1,0,1]
	v_pk_fma_f32 v[108:109], v[108:109], v[126:127], v[120:121] op_sel_hi:[1,0,1]
	v_add_f32_e32 v114, 1.0, v114
	v_add_f32_e32 v115, 1.0, v115
	v_rcp_f32_e32 v114, v114
	v_rcp_f32_e32 v115, v115
	s_nop 0
	v_pk_mul_f32 v[110:111], v[110:111], v[114:115]
	s_nop 0
	v_pk_mul_f32 v[106:107], v[106:107], v[110:111]
	v_pk_fma_f32 v[110:111], v[112:113], v[126:127], v[116:117] op_sel_hi:[1,0,1]
	v_cvt_pk_bf16_f32 v106, v106, v107
	v_mul_f32_e32 v112, 0xbfb8aa3b, v110
	v_mul_f32_e32 v113, 0xbfb8aa3b, v111
	v_exp_f32_e32 v112, v112
	v_exp_f32_e32 v113, v113
	v_lshl_add_u64 v[114:115], v[124:125], 0, v[122:123]
	v_add_f32_e32 v112, 1.0, v112
	v_add_f32_e32 v113, 1.0, v113
	v_rcp_f32_e32 v112, v112
	v_rcp_f32_e32 v113, v113
	s_nop 0
	v_pk_mul_f32 v[110:111], v[110:111], v[112:113]
	s_nop 0
	v_pk_mul_f32 v[108:109], v[108:109], v[110:111]
	s_nop 0
	v_cvt_pk_bf16_f32 v107, v108, v109
	global_store_dwordx2 v[114:115], v[106:107], off
	ds_read_b128 v[106:109], v147 offset:1536
	ds_read_b128 v[110:113], v147 offset:1600
	s_waitcnt lgkmcnt(0)
	v_pk_fma_f32 v[102:103], v[102:103], v[126:127], v[106:107] op_sel_hi:[1,0,1]
	s_nop 0
	v_mul_f32_e32 v106, 0xbfb8aa3b, v102
	v_mul_f32_e32 v107, 0xbfb8aa3b, v103
	v_exp_f32_e32 v106, v106
	v_exp_f32_e32 v107, v107
	v_pk_fma_f32 v[98:99], v[98:99], v[126:127], v[110:111] op_sel_hi:[1,0,1]
	v_pk_fma_f32 v[100:101], v[100:101], v[126:127], v[112:113] op_sel_hi:[1,0,1]
	v_add_f32_e32 v106, 1.0, v106
	v_add_f32_e32 v107, 1.0, v107
	v_rcp_f32_e32 v106, v106
	v_rcp_f32_e32 v107, v107
	s_nop 0
	v_pk_mul_f32 v[102:103], v[102:103], v[106:107]
	s_nop 0
	v_pk_mul_f32 v[98:99], v[98:99], v[102:103]
	v_pk_fma_f32 v[102:103], v[104:105], v[126:127], v[108:109] op_sel_hi:[1,0,1]
	v_cvt_pk_bf16_f32 v98, v98, v99
	v_mul_f32_e32 v104, 0xbfb8aa3b, v102
	v_mul_f32_e32 v105, 0xbfb8aa3b, v103
	v_exp_f32_e32 v104, v104
	v_exp_f32_e32 v105, v105
	v_add_f32_e32 v104, 1.0, v104
	v_add_f32_e32 v105, 1.0, v105
	v_rcp_f32_e32 v104, v104
	v_rcp_f32_e32 v105, v105
	s_nop 0
	v_pk_mul_f32 v[102:103], v[102:103], v[104:105]
	s_nop 0
	v_pk_mul_f32 v[100:101], v[100:101], v[102:103]
	s_nop 0
	v_cvt_pk_bf16_f32 v99, v100, v101
	global_store_dwordx2 v[114:115], v[98:99], off offset:128
	v_or_b32_e32 v98, 32, v136
	v_add_u32_e32 v98, s96, v98
	v_mad_i64_i32 v[106:107], s[98:99], v98, s46, v[132:133]
	ds_read_b32 v98, v148 offset:128
	s_waitcnt lgkmcnt(0)
	v_fmamk_f32 v98, v98, 0x3a800000, v206
	v_cmp_gt_f32_e32 vcc, s35, v98
	v_mul_f32_e32 v99, 0x4b800000, v98
	s_nop 0
	v_cndmask_b32_e32 v98, v98, v99, vcc
	v_rsq_f32_e32 v98, v98
	s_nop 0
	v_mul_f32_e32 v99, 0x45800000, v98
	v_cndmask_b32_e32 v108, v98, v99, vcc
	ds_read_b128 v[98:101], v147 offset:1024
	ds_read_b128 v[102:105], v147 offset:1088
	s_waitcnt lgkmcnt(0)
	v_pk_fma_f32 v[94:95], v[94:95], v[108:109], v[98:99] op_sel_hi:[1,0,1]
	s_nop 0
	v_mul_f32_e32 v98, 0xbfb8aa3b, v94
	v_mul_f32_e32 v99, 0xbfb8aa3b, v95
	v_exp_f32_e32 v98, v98
	v_exp_f32_e32 v99, v99
	v_pk_fma_f32 v[90:91], v[90:91], v[108:109], v[102:103] op_sel_hi:[1,0,1]
	v_pk_fma_f32 v[92:93], v[92:93], v[108:109], v[104:105] op_sel_hi:[1,0,1]
	v_add_f32_e32 v98, 1.0, v98
	v_add_f32_e32 v99, 1.0, v99
	v_rcp_f32_e32 v98, v98
	v_rcp_f32_e32 v99, v99
	s_nop 0
	v_pk_mul_f32 v[94:95], v[94:95], v[98:99]
	s_nop 0
	v_pk_mul_f32 v[90:91], v[90:91], v[94:95]
	v_pk_fma_f32 v[94:95], v[96:97], v[108:109], v[100:101] op_sel_hi:[1,0,1]
	v_cvt_pk_bf16_f32 v90, v90, v91
	v_mul_f32_e32 v96, 0xbfb8aa3b, v94
	v_mul_f32_e32 v97, 0xbfb8aa3b, v95
	v_exp_f32_e32 v96, v96
	v_exp_f32_e32 v97, v97
	v_lshl_add_u64 v[98:99], v[106:107], 0, v[122:123]
	v_add_f32_e32 v96, 1.0, v96
	v_add_f32_e32 v97, 1.0, v97
	v_rcp_f32_e32 v96, v96
	v_rcp_f32_e32 v97, v97
	s_nop 0
	v_pk_mul_f32 v[94:95], v[94:95], v[96:97]
	s_nop 0
	v_pk_mul_f32 v[92:93], v[92:93], v[94:95]
	s_nop 0
	v_cvt_pk_bf16_f32 v91, v92, v93
	global_store_dwordx2 v[98:99], v[90:91], off
	ds_read_b128 v[90:93], v147 offset:1536
	ds_read_b128 v[94:97], v147 offset:1600
	s_waitcnt lgkmcnt(0)
	v_pk_fma_f32 v[86:87], v[86:87], v[108:109], v[90:91] op_sel_hi:[1,0,1]
	s_nop 0
	v_mul_f32_e32 v90, 0xbfb8aa3b, v86
	v_mul_f32_e32 v91, 0xbfb8aa3b, v87
	v_exp_f32_e32 v90, v90
	v_exp_f32_e32 v91, v91
	v_pk_fma_f32 v[82:83], v[82:83], v[108:109], v[94:95] op_sel_hi:[1,0,1]
	v_pk_fma_f32 v[84:85], v[84:85], v[108:109], v[96:97] op_sel_hi:[1,0,1]
	v_add_f32_e32 v90, 1.0, v90
	v_add_f32_e32 v91, 1.0, v91
	v_rcp_f32_e32 v90, v90
	v_rcp_f32_e32 v91, v91
	s_nop 0
	v_pk_mul_f32 v[86:87], v[86:87], v[90:91]
	s_nop 0
	v_pk_mul_f32 v[82:83], v[82:83], v[86:87]
	v_pk_fma_f32 v[86:87], v[88:89], v[108:109], v[92:93] op_sel_hi:[1,0,1]
	v_cvt_pk_bf16_f32 v82, v82, v83
	v_mul_f32_e32 v88, 0xbfb8aa3b, v86
	v_mul_f32_e32 v89, 0xbfb8aa3b, v87
	v_exp_f32_e32 v88, v88
	v_exp_f32_e32 v89, v89
	v_add_f32_e32 v88, 1.0, v88
	v_add_f32_e32 v89, 1.0, v89
	v_rcp_f32_e32 v88, v88
	v_rcp_f32_e32 v89, v89
	s_nop 0
	v_pk_mul_f32 v[86:87], v[86:87], v[88:89]
	s_nop 0
	v_pk_mul_f32 v[84:85], v[84:85], v[86:87]
	s_nop 0
	v_cvt_pk_bf16_f32 v83, v84, v85
	global_store_dwordx2 v[98:99], v[82:83], off offset:128
	v_or_b32_e32 v82, 48, v136
	v_add_u32_e32 v82, s96, v82
	v_mad_i64_i32 v[90:91], s[98:99], v82, s46, v[132:133]
	ds_read_b32 v82, v148 offset:192
	s_waitcnt lgkmcnt(0)
	v_fmamk_f32 v82, v82, 0x3a800000, v206
	v_cmp_gt_f32_e32 vcc, s35, v82
	v_mul_f32_e32 v83, 0x4b800000, v82
	s_nop 0
	v_cndmask_b32_e32 v82, v82, v83, vcc
	v_rsq_f32_e32 v82, v82
	s_nop 0
	v_mul_f32_e32 v83, 0x45800000, v82
	v_cndmask_b32_e32 v92, v82, v83, vcc
	ds_read_b128 v[82:85], v147 offset:1024
	ds_read_b128 v[86:89], v147 offset:1088
	s_waitcnt lgkmcnt(0)
	v_pk_fma_f32 v[78:79], v[78:79], v[92:93], v[82:83] op_sel_hi:[1,0,1]
	s_nop 0
	v_mul_f32_e32 v82, 0xbfb8aa3b, v78
	v_mul_f32_e32 v83, 0xbfb8aa3b, v79
	v_exp_f32_e32 v82, v82
	v_exp_f32_e32 v83, v83
	v_pk_fma_f32 v[74:75], v[74:75], v[92:93], v[86:87] op_sel_hi:[1,0,1]
	v_pk_fma_f32 v[76:77], v[76:77], v[92:93], v[88:89] op_sel_hi:[1,0,1]
	v_add_f32_e32 v82, 1.0, v82
	v_add_f32_e32 v83, 1.0, v83
	v_rcp_f32_e32 v82, v82
	v_rcp_f32_e32 v83, v83
	s_nop 0
	v_pk_mul_f32 v[78:79], v[78:79], v[82:83]
	s_nop 0
	v_pk_mul_f32 v[74:75], v[74:75], v[78:79]
	v_pk_fma_f32 v[78:79], v[80:81], v[92:93], v[84:85] op_sel_hi:[1,0,1]
	v_cvt_pk_bf16_f32 v74, v74, v75
	v_mul_f32_e32 v80, 0xbfb8aa3b, v78
	v_mul_f32_e32 v81, 0xbfb8aa3b, v79
	v_exp_f32_e32 v80, v80
	v_exp_f32_e32 v81, v81
	v_lshl_add_u64 v[82:83], v[90:91], 0, v[122:123]
	v_add_f32_e32 v80, 1.0, v80
	v_add_f32_e32 v81, 1.0, v81
	v_rcp_f32_e32 v80, v80
	v_rcp_f32_e32 v81, v81
	s_nop 0
	v_pk_mul_f32 v[78:79], v[78:79], v[80:81]
	s_nop 0
	v_pk_mul_f32 v[76:77], v[76:77], v[78:79]
	s_nop 0
	v_cvt_pk_bf16_f32 v75, v76, v77
	global_store_dwordx2 v[82:83], v[74:75], off
	ds_read_b128 v[74:77], v147 offset:1536
	ds_read_b128 v[78:81], v147 offset:1600
	s_waitcnt lgkmcnt(0)
	v_pk_fma_f32 v[70:71], v[70:71], v[92:93], v[74:75] op_sel_hi:[1,0,1]
	s_nop 0
	v_mul_f32_e32 v74, 0xbfb8aa3b, v70
	v_mul_f32_e32 v75, 0xbfb8aa3b, v71
	v_exp_f32_e32 v74, v74
	v_exp_f32_e32 v75, v75
	v_pk_fma_f32 v[66:67], v[66:67], v[92:93], v[78:79] op_sel_hi:[1,0,1]
	v_pk_fma_f32 v[68:69], v[68:69], v[92:93], v[80:81] op_sel_hi:[1,0,1]
	v_add_f32_e32 v74, 1.0, v74
	v_add_f32_e32 v75, 1.0, v75
	v_rcp_f32_e32 v74, v74
	v_rcp_f32_e32 v75, v75
	s_nop 0
	v_pk_mul_f32 v[70:71], v[70:71], v[74:75]
	s_nop 0
	v_pk_mul_f32 v[66:67], v[66:67], v[70:71]
	v_pk_fma_f32 v[70:71], v[72:73], v[92:93], v[76:77] op_sel_hi:[1,0,1]
	v_cvt_pk_bf16_f32 v66, v66, v67
	v_mul_f32_e32 v72, 0xbfb8aa3b, v70
	v_mul_f32_e32 v73, 0xbfb8aa3b, v71
	v_exp_f32_e32 v72, v72
	v_exp_f32_e32 v73, v73
	v_add_f32_e32 v72, 1.0, v72
	v_add_f32_e32 v73, 1.0, v73
	v_rcp_f32_e32 v72, v72
	v_rcp_f32_e32 v73, v73
	s_nop 0
	v_pk_mul_f32 v[70:71], v[70:71], v[72:73]
	s_nop 0
	v_pk_mul_f32 v[68:69], v[68:69], v[70:71]
	s_nop 0
	v_cvt_pk_bf16_f32 v67, v68, v69
	global_store_dwordx2 v[82:83], v[66:67], off offset:128
	v_add_u32_e32 v66, 0x80, v136
	v_add_u32_e32 v66, s96, v66
	v_mad_i64_i32 v[74:75], s[98:99], v66, s46, v[132:133]
	ds_read_b32 v66, v148 offset:512
	s_waitcnt lgkmcnt(0)
	v_fmamk_f32 v66, v66, 0x3a800000, v206
	v_cmp_gt_f32_e32 vcc, s35, v66
	v_mul_f32_e32 v67, 0x4b800000, v66
	s_nop 0
	v_cndmask_b32_e32 v66, v66, v67, vcc
	v_rsq_f32_e32 v66, v66
	s_nop 0
	v_mul_f32_e32 v67, 0x45800000, v66
	v_cndmask_b32_e32 v76, v66, v67, vcc
	ds_read_b128 v[66:69], v147 offset:1024
	ds_read_b128 v[70:73], v147 offset:1088
	s_waitcnt lgkmcnt(0)
	v_pk_fma_f32 v[62:63], v[62:63], v[76:77], v[66:67] op_sel_hi:[1,0,1]
	s_nop 0
	v_mul_f32_e32 v66, 0xbfb8aa3b, v62
	v_mul_f32_e32 v67, 0xbfb8aa3b, v63
	v_exp_f32_e32 v66, v66
	v_exp_f32_e32 v67, v67
	v_pk_fma_f32 v[58:59], v[58:59], v[76:77], v[70:71] op_sel_hi:[1,0,1]
	v_pk_fma_f32 v[60:61], v[60:61], v[76:77], v[72:73] op_sel_hi:[1,0,1]
	v_add_f32_e32 v66, 1.0, v66
	v_add_f32_e32 v67, 1.0, v67
	v_rcp_f32_e32 v66, v66
	v_rcp_f32_e32 v67, v67
	s_nop 0
	v_pk_mul_f32 v[62:63], v[62:63], v[66:67]
	s_nop 0
	v_pk_mul_f32 v[58:59], v[58:59], v[62:63]
	v_pk_fma_f32 v[62:63], v[64:65], v[76:77], v[68:69] op_sel_hi:[1,0,1]
	v_cvt_pk_bf16_f32 v58, v58, v59
	v_mul_f32_e32 v64, 0xbfb8aa3b, v62
	v_mul_f32_e32 v65, 0xbfb8aa3b, v63
	v_exp_f32_e32 v64, v64
	v_exp_f32_e32 v65, v65
	v_lshl_add_u64 v[66:67], v[74:75], 0, v[122:123]
	v_add_f32_e32 v64, 1.0, v64
	v_add_f32_e32 v65, 1.0, v65
	v_rcp_f32_e32 v64, v64
	v_rcp_f32_e32 v65, v65
	s_nop 0
	v_pk_mul_f32 v[62:63], v[62:63], v[64:65]
	s_nop 0
	v_pk_mul_f32 v[60:61], v[60:61], v[62:63]
	s_nop 0
	v_cvt_pk_bf16_f32 v59, v60, v61
	global_store_dwordx2 v[66:67], v[58:59], off
	ds_read_b128 v[58:61], v147 offset:1536
	ds_read_b128 v[62:65], v147 offset:1600
	s_waitcnt lgkmcnt(0)
	v_pk_fma_f32 v[54:55], v[54:55], v[76:77], v[58:59] op_sel_hi:[1,0,1]
	s_nop 0
	v_mul_f32_e32 v58, 0xbfb8aa3b, v54
	v_mul_f32_e32 v59, 0xbfb8aa3b, v55
	v_exp_f32_e32 v58, v58
	v_exp_f32_e32 v59, v59
	v_pk_fma_f32 v[50:51], v[50:51], v[76:77], v[62:63] op_sel_hi:[1,0,1]
	v_pk_fma_f32 v[52:53], v[52:53], v[76:77], v[64:65] op_sel_hi:[1,0,1]
	v_add_f32_e32 v58, 1.0, v58
	v_add_f32_e32 v59, 1.0, v59
	v_rcp_f32_e32 v58, v58
	v_rcp_f32_e32 v59, v59
	s_nop 0
	v_pk_mul_f32 v[54:55], v[54:55], v[58:59]
	s_nop 0
	v_pk_mul_f32 v[50:51], v[50:51], v[54:55]
	v_pk_fma_f32 v[54:55], v[56:57], v[76:77], v[60:61] op_sel_hi:[1,0,1]
	v_cvt_pk_bf16_f32 v50, v50, v51
	v_mul_f32_e32 v56, 0xbfb8aa3b, v54
	v_mul_f32_e32 v57, 0xbfb8aa3b, v55
	v_exp_f32_e32 v56, v56
	v_exp_f32_e32 v57, v57
	v_add_f32_e32 v56, 1.0, v56
	v_add_f32_e32 v57, 1.0, v57
	v_rcp_f32_e32 v56, v56
	v_rcp_f32_e32 v57, v57
	s_nop 0
	v_pk_mul_f32 v[54:55], v[54:55], v[56:57]
	s_nop 0
	v_pk_mul_f32 v[52:53], v[52:53], v[54:55]
	s_nop 0
	v_cvt_pk_bf16_f32 v51, v52, v53
	global_store_dwordx2 v[66:67], v[50:51], off offset:128
	v_add_u32_e32 v50, 0x90, v136
	v_add_u32_e32 v50, s96, v50
	v_mad_i64_i32 v[58:59], s[98:99], v50, s46, v[132:133]
	ds_read_b32 v50, v148 offset:576
	s_waitcnt lgkmcnt(0)
	v_fmamk_f32 v50, v50, 0x3a800000, v206
	v_cmp_gt_f32_e32 vcc, s35, v50
	v_mul_f32_e32 v51, 0x4b800000, v50
	s_nop 0
	v_cndmask_b32_e32 v50, v50, v51, vcc
	v_rsq_f32_e32 v50, v50
	s_nop 0
	v_mul_f32_e32 v51, 0x45800000, v50
	v_cndmask_b32_e32 v60, v50, v51, vcc
	ds_read_b128 v[50:53], v147 offset:1024
	ds_read_b128 v[54:57], v147 offset:1088
	s_waitcnt lgkmcnt(0)
	v_pk_fma_f32 v[46:47], v[46:47], v[60:61], v[50:51] op_sel_hi:[1,0,1]
	s_nop 0
	v_mul_f32_e32 v50, 0xbfb8aa3b, v46
	v_mul_f32_e32 v51, 0xbfb8aa3b, v47
	v_exp_f32_e32 v50, v50
	v_exp_f32_e32 v51, v51
	v_pk_fma_f32 v[42:43], v[42:43], v[60:61], v[54:55] op_sel_hi:[1,0,1]
	v_pk_fma_f32 v[44:45], v[44:45], v[60:61], v[56:57] op_sel_hi:[1,0,1]
	v_add_f32_e32 v50, 1.0, v50
	v_add_f32_e32 v51, 1.0, v51
	v_rcp_f32_e32 v50, v50
	v_rcp_f32_e32 v51, v51
	s_nop 0
	v_pk_mul_f32 v[46:47], v[46:47], v[50:51]
	s_nop 0
	v_pk_mul_f32 v[42:43], v[42:43], v[46:47]
	v_pk_fma_f32 v[46:47], v[48:49], v[60:61], v[52:53] op_sel_hi:[1,0,1]
	v_cvt_pk_bf16_f32 v42, v42, v43
	v_mul_f32_e32 v48, 0xbfb8aa3b, v46
	v_mul_f32_e32 v49, 0xbfb8aa3b, v47
	v_exp_f32_e32 v48, v48
	v_exp_f32_e32 v49, v49
	v_lshl_add_u64 v[50:51], v[58:59], 0, v[122:123]
	v_add_f32_e32 v48, 1.0, v48
	v_add_f32_e32 v49, 1.0, v49
	v_rcp_f32_e32 v48, v48
	v_rcp_f32_e32 v49, v49
	s_nop 0
	v_pk_mul_f32 v[46:47], v[46:47], v[48:49]
	s_nop 0
	v_pk_mul_f32 v[44:45], v[44:45], v[46:47]
	s_nop 0
	v_cvt_pk_bf16_f32 v43, v44, v45
	global_store_dwordx2 v[50:51], v[42:43], off
	ds_read_b128 v[42:45], v147 offset:1536
	ds_read_b128 v[46:49], v147 offset:1600
	s_waitcnt lgkmcnt(0)
	v_pk_fma_f32 v[38:39], v[38:39], v[60:61], v[42:43] op_sel_hi:[1,0,1]
	s_nop 0
	v_mul_f32_e32 v42, 0xbfb8aa3b, v38
	v_mul_f32_e32 v43, 0xbfb8aa3b, v39
	v_exp_f32_e32 v42, v42
	v_exp_f32_e32 v43, v43
	v_pk_fma_f32 v[34:35], v[34:35], v[60:61], v[46:47] op_sel_hi:[1,0,1]
	v_pk_fma_f32 v[36:37], v[36:37], v[60:61], v[48:49] op_sel_hi:[1,0,1]
	v_add_f32_e32 v42, 1.0, v42
	v_add_f32_e32 v43, 1.0, v43
	v_rcp_f32_e32 v42, v42
	v_rcp_f32_e32 v43, v43
	s_nop 0
	v_pk_mul_f32 v[38:39], v[38:39], v[42:43]
	s_nop 0
	v_pk_mul_f32 v[34:35], v[34:35], v[38:39]
	v_pk_fma_f32 v[38:39], v[40:41], v[60:61], v[44:45] op_sel_hi:[1,0,1]
	v_cvt_pk_bf16_f32 v34, v34, v35
	v_mul_f32_e32 v40, 0xbfb8aa3b, v38
	v_mul_f32_e32 v41, 0xbfb8aa3b, v39
	v_exp_f32_e32 v40, v40
	v_exp_f32_e32 v41, v41
	v_add_f32_e32 v40, 1.0, v40
	v_add_f32_e32 v41, 1.0, v41
	v_rcp_f32_e32 v40, v40
	v_rcp_f32_e32 v41, v41
	s_nop 0
	v_pk_mul_f32 v[38:39], v[38:39], v[40:41]
	s_nop 0
	v_pk_mul_f32 v[36:37], v[36:37], v[38:39]
	s_nop 0
	v_cvt_pk_bf16_f32 v35, v36, v37
	global_store_dwordx2 v[50:51], v[34:35], off offset:128
	v_add_u32_e32 v34, 0xa0, v136
	v_add_u32_e32 v34, s96, v34
	v_mad_i64_i32 v[42:43], s[98:99], v34, s46, v[132:133]
	ds_read_b32 v34, v148 offset:640
	s_waitcnt lgkmcnt(0)
	v_fmamk_f32 v34, v34, 0x3a800000, v206
	v_cmp_gt_f32_e32 vcc, s35, v34
	v_mul_f32_e32 v35, 0x4b800000, v34
	s_nop 0
	v_cndmask_b32_e32 v34, v34, v35, vcc
	v_rsq_f32_e32 v34, v34
	s_nop 0
	v_mul_f32_e32 v35, 0x45800000, v34
	v_cndmask_b32_e32 v44, v34, v35, vcc
	ds_read_b128 v[34:37], v147 offset:1024
	ds_read_b128 v[38:41], v147 offset:1088
	s_waitcnt lgkmcnt(0)
	v_pk_fma_f32 v[30:31], v[30:31], v[44:45], v[34:35] op_sel_hi:[1,0,1]
	s_nop 0
	v_mul_f32_e32 v34, 0xbfb8aa3b, v30
	v_mul_f32_e32 v35, 0xbfb8aa3b, v31
	v_exp_f32_e32 v34, v34
	v_exp_f32_e32 v35, v35
	v_pk_fma_f32 v[26:27], v[26:27], v[44:45], v[38:39] op_sel_hi:[1,0,1]
	v_pk_fma_f32 v[28:29], v[28:29], v[44:45], v[40:41] op_sel_hi:[1,0,1]
	v_add_f32_e32 v34, 1.0, v34
	v_add_f32_e32 v35, 1.0, v35
	v_rcp_f32_e32 v34, v34
	v_rcp_f32_e32 v35, v35
	s_nop 0
	v_pk_mul_f32 v[30:31], v[30:31], v[34:35]
	s_nop 0
	v_pk_mul_f32 v[26:27], v[26:27], v[30:31]
	v_pk_fma_f32 v[30:31], v[32:33], v[44:45], v[36:37] op_sel_hi:[1,0,1]
	v_cvt_pk_bf16_f32 v26, v26, v27
	v_mul_f32_e32 v32, 0xbfb8aa3b, v30
	v_mul_f32_e32 v33, 0xbfb8aa3b, v31
	v_exp_f32_e32 v32, v32
	v_exp_f32_e32 v33, v33
	v_lshl_add_u64 v[34:35], v[42:43], 0, v[122:123]
	v_add_f32_e32 v32, 1.0, v32
	v_add_f32_e32 v33, 1.0, v33
	v_rcp_f32_e32 v32, v32
	v_rcp_f32_e32 v33, v33
	s_nop 0
	v_pk_mul_f32 v[30:31], v[30:31], v[32:33]
	s_nop 0
	v_pk_mul_f32 v[28:29], v[28:29], v[30:31]
	s_nop 0
	v_cvt_pk_bf16_f32 v27, v28, v29
	global_store_dwordx2 v[34:35], v[26:27], off
	ds_read_b128 v[26:29], v147 offset:1536
	ds_read_b128 v[30:33], v147 offset:1600
	s_waitcnt lgkmcnt(0)
	v_pk_fma_f32 v[22:23], v[22:23], v[44:45], v[26:27] op_sel_hi:[1,0,1]
	s_nop 0
	v_mul_f32_e32 v26, 0xbfb8aa3b, v22
	v_mul_f32_e32 v27, 0xbfb8aa3b, v23
	v_exp_f32_e32 v26, v26
	v_exp_f32_e32 v27, v27
	v_pk_fma_f32 v[18:19], v[18:19], v[44:45], v[30:31] op_sel_hi:[1,0,1]
	v_pk_fma_f32 v[20:21], v[20:21], v[44:45], v[32:33] op_sel_hi:[1,0,1]
	v_add_f32_e32 v26, 1.0, v26
	v_add_f32_e32 v27, 1.0, v27
	v_rcp_f32_e32 v26, v26
	v_rcp_f32_e32 v27, v27
	s_nop 0
	v_pk_mul_f32 v[22:23], v[22:23], v[26:27]
	s_nop 0
	v_pk_mul_f32 v[18:19], v[18:19], v[22:23]
	v_pk_fma_f32 v[22:23], v[24:25], v[44:45], v[28:29] op_sel_hi:[1,0,1]
	v_cvt_pk_bf16_f32 v18, v18, v19
	v_mul_f32_e32 v24, 0xbfb8aa3b, v22
	v_mul_f32_e32 v25, 0xbfb8aa3b, v23
	v_exp_f32_e32 v24, v24
	v_exp_f32_e32 v25, v25
	v_add_f32_e32 v24, 1.0, v24
	v_add_f32_e32 v25, 1.0, v25
	v_rcp_f32_e32 v24, v24
	v_rcp_f32_e32 v25, v25
	s_nop 0
	v_pk_mul_f32 v[22:23], v[22:23], v[24:25]
	s_nop 0
	v_pk_mul_f32 v[20:21], v[20:21], v[22:23]
	s_nop 0
	v_cvt_pk_bf16_f32 v19, v20, v21
	global_store_dwordx2 v[34:35], v[18:19], off offset:128
	v_add_u32_e32 v18, 0xb0, v136
	v_add_u32_e32 v18, s96, v18
	v_mad_i64_i32 v[26:27], s[98:99], v18, s46, v[132:133]
	ds_read_b32 v18, v148 offset:704
	s_waitcnt lgkmcnt(0)
	v_fmamk_f32 v18, v18, 0x3a800000, v206
	v_cmp_gt_f32_e32 vcc, s35, v18
	v_mul_f32_e32 v19, 0x4b800000, v18
	s_nop 0
	v_cndmask_b32_e32 v18, v18, v19, vcc
	v_rsq_f32_e32 v18, v18
	s_nop 0
	v_mul_f32_e32 v19, 0x45800000, v18
	v_cndmask_b32_e32 v28, v18, v19, vcc
	ds_read_b128 v[18:21], v147 offset:1024
	ds_read_b128 v[22:25], v147 offset:1088
	s_waitcnt lgkmcnt(0)
	v_pk_fma_f32 v[14:15], v[14:15], v[28:29], v[18:19] op_sel_hi:[1,0,1]
	s_nop 0
	v_mul_f32_e32 v18, 0xbfb8aa3b, v14
	v_mul_f32_e32 v19, 0xbfb8aa3b, v15
	v_exp_f32_e32 v18, v18
	v_exp_f32_e32 v19, v19
	v_pk_fma_f32 v[10:11], v[10:11], v[28:29], v[22:23] op_sel_hi:[1,0,1]
	v_pk_fma_f32 v[12:13], v[12:13], v[28:29], v[24:25] op_sel_hi:[1,0,1]
	v_add_f32_e32 v18, 1.0, v18
	v_add_f32_e32 v19, 1.0, v19
	v_rcp_f32_e32 v18, v18
	v_rcp_f32_e32 v19, v19
	s_nop 0
	v_pk_mul_f32 v[14:15], v[14:15], v[18:19]
	s_nop 0
	v_pk_mul_f32 v[10:11], v[10:11], v[14:15]
	v_pk_fma_f32 v[14:15], v[16:17], v[28:29], v[20:21] op_sel_hi:[1,0,1]
	v_cvt_pk_bf16_f32 v10, v10, v11
	v_mul_f32_e32 v16, 0xbfb8aa3b, v14
	v_mul_f32_e32 v17, 0xbfb8aa3b, v15
	v_exp_f32_e32 v16, v16
	v_exp_f32_e32 v17, v17
	v_lshl_add_u64 v[18:19], v[26:27], 0, v[122:123]
	v_add_f32_e32 v16, 1.0, v16
	v_add_f32_e32 v17, 1.0, v17
	v_rcp_f32_e32 v16, v16
	v_rcp_f32_e32 v17, v17
	s_nop 0
	v_pk_mul_f32 v[14:15], v[14:15], v[16:17]
	s_nop 0
	v_pk_mul_f32 v[12:13], v[12:13], v[14:15]
	s_nop 0
	v_cvt_pk_bf16_f32 v11, v12, v13
	global_store_dwordx2 v[18:19], v[10:11], off
	ds_read_b128 v[10:13], v147 offset:1536
	ds_read_b128 v[14:17], v147 offset:1600
	s_waitcnt lgkmcnt(0)
	v_pk_fma_f32 v[6:7], v[6:7], v[28:29], v[10:11] op_sel_hi:[1,0,1]
	s_nop 0
	v_mul_f32_e32 v10, 0xbfb8aa3b, v6
	v_mul_f32_e32 v11, 0xbfb8aa3b, v7
	v_exp_f32_e32 v10, v10
	v_exp_f32_e32 v11, v11
	v_pk_fma_f32 v[2:3], v[2:3], v[28:29], v[14:15] op_sel_hi:[1,0,1]
	v_pk_fma_f32 v[4:5], v[4:5], v[28:29], v[16:17] op_sel_hi:[1,0,1]
	v_add_f32_e32 v10, 1.0, v10
	v_add_f32_e32 v11, 1.0, v11
	v_rcp_f32_e32 v10, v10
	v_rcp_f32_e32 v11, v11
	s_nop 0
	v_pk_mul_f32 v[6:7], v[6:7], v[10:11]
	s_nop 0
	v_pk_mul_f32 v[2:3], v[2:3], v[6:7]
	v_pk_fma_f32 v[6:7], v[8:9], v[28:29], v[12:13] op_sel_hi:[1,0,1]
	v_cvt_pk_bf16_f32 v2, v2, v3
	v_mul_f32_e32 v8, 0xbfb8aa3b, v6
	v_mul_f32_e32 v9, 0xbfb8aa3b, v7
	v_exp_f32_e32 v8, v8
	v_exp_f32_e32 v9, v9
	v_add_f32_e32 v8, 1.0, v8
	v_add_f32_e32 v9, 1.0, v9
	v_rcp_f32_e32 v8, v8
	v_rcp_f32_e32 v9, v9
	s_nop 0
	v_pk_mul_f32 v[6:7], v[6:7], v[8:9]
	s_nop 0
	v_pk_mul_f32 v[4:5], v[4:5], v[6:7]
	s_nop 0
	v_cvt_pk_bf16_f32 v3, v4, v5
	global_store_dwordx2 v[18:19], v[2:3], off offset:128
	s_cmp_eq_u32 s72, 0
	s_cbranch_scc1 .LBB0_1565
	v_add_u32_e32 v132, s33, v135
	v_add_u32_e32 v133, 0x2000, v132
	v_add_u32_e32 v147, 0x400, v135
	v_add_u32_e32 v148, 0x2000, v147
	v_add_u32_e32 v149, s52, v135
	v_add_u32_e32 v150, 0x2000, v149
	v_add_u32_e32 v151, 0x4000, v147
	v_add_u32_e32 v152, 0x6000, v147
	v_mov_b32_e32 v4, v238
	v_mov_b32_e32 v5, v239
	s_branch .Lhr_after_dma

.Lhr_after_dma:
	s_waitcnt vmcnt(8)
	ds_write_b32 v5, v4
	s_waitcnt lgkmcnt(0)
	s_barrier
	s_and_saveexec_b64 s[40:41], s[2:3]
	s_cbranch_execz .LBB0_1561
	s_barrier
